# v25 + GEMM first-half-K-tile peeled with SrcC=0 (no accumulator zeroing, UP+QKV) + UP epilogue without canonicalising max
# speedup vs baseline: 1.0145x; 1.0019x over previous
.LBB0_158:
	s_ashr_i32 s45, s44, 31
	s_lshl_b64 s[46:47], s[44:45], 19
	s_add_u32 s46, s90, s46
	s_addc_u32 s47, s91, s47
	s_and_b64 s[58:59], s[42:43], exec
	s_cselect_b32 s12, s47, s65
	s_cselect_b32 s45, s46, s64
	s_ashr_i32 s11, s10, 31
	s_lshl_b64 s[58:59], s[10:11], 19
	s_add_u32 s58, s14, s58
	s_addc_u32 s59, s15, s59
	s_and_b64 s[66:67], s[42:43], exec
	s_cselect_b32 s11, s59, s63
	s_cselect_b32 s73, s58, s62
	s_add_u32 s74, s62, 0x100
	s_addc_u32 s75, s63, 0
	s_add_u32 s62, s64, 0x40080
	s_addc_u32 s63, s65, 0
	s_mov_b32 s84, -2
	s_waitcnt lgkmcnt(0)
	s_add_u32 s3, s62, 0xfffc0080
	s_addc_u32 s64, s63, -1
	s_add_i32 s85, 0, 0x10000
	s_cmp_eq_u32 s84, 12
	s_cselect_b32 s67, s12, s64
	s_cselect_b32 s66, s45, s3
	v_add_u32_e32 v140, s85, v143
	s_cselect_b32 s65, s11, s75
	s_cselect_b32 s64, s73, s74
	s_add_i32 s3, 0, 0x14000
	ds_read_b128 v[152:155], v140
	ds_read_b128 v[156:159], v140 offset:1024
	ds_read_b128 v[160:163], v140 offset:2048
	ds_read_b128 v[164:167], v140 offset:3072
	v_add_u32_e32 v140, s3, v143
	ds_read_b128 v[168:171], v140
	ds_read_b128 v[172:175], v140 offset:1024
	ds_read_b128 v[176:179], v140 offset:2048
	ds_read_b128 v[180:183], v140 offset:3072
	v_lshl_add_u64 v[140:141], s[62:63], 0, v[138:139]
	s_add_i32 m0, s17, 0xc000
	ds_read_b128 v[184:187], v150
	ds_read_b128 v[188:191], v150 offset:1024
	ds_read_b128 v[192:195], v150 offset:2048
	ds_read_b128 v[226:229], v150 offset:3072
	ds_read_b128 v[230:233], v150 offset:4096
	ds_read_b128 v[234:237], v150 offset:5120
	ds_read_b128 v[238:241], v150 offset:6144
	ds_read_b128 v[242:245], v150 offset:7168
	global_load_lds_dwordx4 v[140:141], off
	v_lshl_add_u64 v[140:141], s[62:63], 0, v[136:137]
	s_add_i32 m0, s17, 0xe000
	s_nop 0
	global_load_lds_dwordx4 v[140:141], off
	s_waitcnt vmcnt(8)
	s_waitcnt lgkmcnt(0)
	s_barrier
	s_setprio 1
	s_waitcnt lgkmcnt(0)
	v_mfma_f32_16x16x32_bf16 v[122:125], v[152:155], v[184:187], 0
	v_mfma_f32_16x16x32_bf16 v[126:129], v[160:163], v[184:187], 0
	v_mfma_f32_16x16x32_bf16 v[106:109], v[152:155], v[192:195], 0
	v_mfma_f32_16x16x32_bf16 v[110:113], v[160:163], v[192:195], 0
	v_mfma_f32_16x16x32_bf16 v[90:93], v[152:155], v[230:233], 0
	v_mfma_f32_16x16x32_bf16 v[94:97], v[160:163], v[230:233], 0
	v_mfma_f32_16x16x32_bf16 v[74:77], v[152:155], v[238:241], 0
	v_mfma_f32_16x16x32_bf16 v[78:81], v[160:163], v[238:241], 0
	v_mfma_f32_16x16x32_bf16 v[122:125], v[156:159], v[188:191], v[122:125]
	v_mfma_f32_16x16x32_bf16 v[126:129], v[164:167], v[188:191], v[126:129]
	v_mfma_f32_16x16x32_bf16 v[106:109], v[156:159], v[226:229], v[106:109]
	v_mfma_f32_16x16x32_bf16 v[110:113], v[164:167], v[226:229], v[110:113]
	v_mfma_f32_16x16x32_bf16 v[90:93], v[156:159], v[234:237], v[90:93]
	v_mfma_f32_16x16x32_bf16 v[94:97], v[164:167], v[234:237], v[94:97]
	v_mfma_f32_16x16x32_bf16 v[74:77], v[156:159], v[242:245], v[74:77]
	v_mfma_f32_16x16x32_bf16 v[78:81], v[164:167], v[242:245], v[78:81]
	s_setprio 0
	s_setprio 1
	v_mfma_f32_16x16x32_bf16 v[114:117], v[168:171], v[184:187], 0
	v_mfma_f32_16x16x32_bf16 v[118:121], v[176:179], v[184:187], 0
	v_mfma_f32_16x16x32_bf16 v[98:101], v[168:171], v[192:195], 0
	v_mfma_f32_16x16x32_bf16 v[102:105], v[176:179], v[192:195], 0
	v_mfma_f32_16x16x32_bf16 v[82:85], v[168:171], v[230:233], 0
	v_mfma_f32_16x16x32_bf16 v[86:89], v[176:179], v[230:233], 0
	v_mfma_f32_16x16x32_bf16 v[66:69], v[168:171], v[238:241], 0
	v_mfma_f32_16x16x32_bf16 v[70:73], v[176:179], v[238:241], 0
	v_mfma_f32_16x16x32_bf16 v[114:117], v[172:175], v[188:191], v[114:117]
	v_mfma_f32_16x16x32_bf16 v[118:121], v[180:183], v[188:191], v[118:121]
	v_mfma_f32_16x16x32_bf16 v[98:101], v[172:175], v[226:229], v[98:101]
	v_mfma_f32_16x16x32_bf16 v[102:105], v[180:183], v[226:229], v[102:105]
	v_mfma_f32_16x16x32_bf16 v[82:85], v[172:175], v[234:237], v[82:85]
	v_mfma_f32_16x16x32_bf16 v[86:89], v[180:183], v[234:237], v[86:89]
	v_mfma_f32_16x16x32_bf16 v[66:69], v[172:175], v[242:245], v[66:69]
	v_mfma_f32_16x16x32_bf16 v[70:73], v[180:183], v[242:245], v[70:73]
	s_setprio 0
	s_barrier
	s_add_i32 s85, s85, s16
	v_lshl_add_u64 v[140:141], s[64:65], 0, v[144:145]
	s_mov_b32 m0, s85
	ds_read_b128 v[184:187], v150 offset:16384
	ds_read_b128 v[188:191], v150 offset:17408
	ds_read_b128 v[192:195], v150 offset:18432
	ds_read_b128 v[226:229], v150 offset:19456
	ds_read_b128 v[230:233], v150 offset:20480
	ds_read_b128 v[234:237], v150 offset:21504
	ds_read_b128 v[238:241], v150 offset:22528
	ds_read_b128 v[242:245], v150 offset:23552
	global_load_lds_dwordx4 v[140:141], off
	s_add_i32 m0, s85, 0x2000
	s_add_u32 s86, s64, 0x40000
	v_lshl_add_u64 v[196:197], s[64:65], 0, v[130:131]
	s_addc_u32 s87, s65, 0
	s_add_i32 s3, s3, s16
	global_load_lds_dwordx4 v[196:197], off
	v_lshl_add_u64 v[206:207], s[86:87], 0, v[144:145]
	s_mov_b32 m0, s3
	v_lshl_add_u64 v[210:211], s[66:67], 0, v[132:133]
	global_load_lds_dwordx4 v[206:207], off
	v_lshl_add_u64 v[206:207], s[86:87], 0, v[130:131]
	s_add_i32 m0, s3, 0x2000
	s_nop 0
	global_load_lds_dwordx4 v[206:207], off
	v_lshl_add_u64 v[206:207], s[66:67], 0, v[134:135]
	s_mov_b32 m0, s17
	s_nop 0
	global_load_lds_dwordx4 v[206:207], off
	s_mov_b32 m0, s18
	s_nop 0
	global_load_lds_dwordx4 v[210:211], off
	s_waitcnt vmcnt(8)
	s_waitcnt lgkmcnt(0)
	s_barrier
	s_setprio 1
	s_waitcnt lgkmcnt(0)
	v_mfma_f32_16x16x32_bf16 v[58:61], v[152:155], v[184:187], 0
	v_mfma_f32_16x16x32_bf16 v[62:65], v[160:163], v[184:187], 0
	v_mfma_f32_16x16x32_bf16 v[42:45], v[152:155], v[192:195], 0
	v_mfma_f32_16x16x32_bf16 v[46:49], v[160:163], v[192:195], 0
	v_mfma_f32_16x16x32_bf16 v[26:29], v[152:155], v[230:233], 0
	v_mfma_f32_16x16x32_bf16 v[30:33], v[160:163], v[230:233], 0
	v_mfma_f32_16x16x32_bf16 v[10:13], v[152:155], v[238:241], 0
	v_mfma_f32_16x16x32_bf16 v[14:17], v[160:163], v[238:241], 0
	v_mfma_f32_16x16x32_bf16 v[58:61], v[156:159], v[188:191], v[58:61]
	v_mfma_f32_16x16x32_bf16 v[62:65], v[164:167], v[188:191], v[62:65]
	v_mfma_f32_16x16x32_bf16 v[42:45], v[156:159], v[226:229], v[42:45]
	v_mfma_f32_16x16x32_bf16 v[46:49], v[164:167], v[226:229], v[46:49]
	v_mfma_f32_16x16x32_bf16 v[26:29], v[156:159], v[234:237], v[26:29]
	v_mfma_f32_16x16x32_bf16 v[30:33], v[164:167], v[234:237], v[30:33]
	v_mfma_f32_16x16x32_bf16 v[10:13], v[156:159], v[242:245], v[10:13]
	v_mfma_f32_16x16x32_bf16 v[14:17], v[164:167], v[242:245], v[14:17]
	s_setprio 0
	s_setprio 1
	v_mfma_f32_16x16x32_bf16 v[50:53], v[168:171], v[184:187], 0
	v_mfma_f32_16x16x32_bf16 v[54:57], v[176:179], v[184:187], 0
	v_mfma_f32_16x16x32_bf16 v[34:37], v[168:171], v[192:195], 0
	v_mfma_f32_16x16x32_bf16 v[38:41], v[176:179], v[192:195], 0
	v_mfma_f32_16x16x32_bf16 v[18:21], v[168:171], v[230:233], 0
	v_mfma_f32_16x16x32_bf16 v[22:25], v[176:179], v[230:233], 0
	v_mfma_f32_16x16x32_bf16 v[0:3], v[168:171], v[238:241], 0
	v_mfma_f32_16x16x32_bf16 v[4:7], v[176:179], v[238:241], 0
	v_mfma_f32_16x16x32_bf16 v[50:53], v[172:175], v[188:191], v[50:53]
	v_mfma_f32_16x16x32_bf16 v[54:57], v[180:183], v[188:191], v[54:57]
	v_mfma_f32_16x16x32_bf16 v[34:37], v[172:175], v[226:229], v[34:37]
	v_mfma_f32_16x16x32_bf16 v[38:41], v[180:183], v[226:229], v[38:41]
	v_mfma_f32_16x16x32_bf16 v[18:21], v[172:175], v[234:237], v[18:21]
	v_mfma_f32_16x16x32_bf16 v[22:25], v[180:183], v[234:237], v[22:25]
	v_mfma_f32_16x16x32_bf16 v[0:3], v[172:175], v[242:245], v[0:3]
	v_mfma_f32_16x16x32_bf16 v[4:7], v[180:183], v[242:245], v[4:7]
	s_setprio 0
	s_barrier
	s_branch .Lgemm_mid_0

.Lgemm_mid_0:
	s_add_i32 s3, 0, 0x18000
	v_add_u32_e32 v151, s3, v143
	s_add_i32 s85, 0, 0x1c000
	ds_read_b128 v[152:155], v151
	ds_read_b128 v[156:159], v151 offset:1024
	ds_read_b128 v[160:163], v151 offset:2048
	ds_read_b128 v[164:167], v151 offset:3072
	v_add_u32_e32 v151, s85, v143
	ds_read_b128 v[168:171], v151
	ds_read_b128 v[172:175], v151 offset:1024
	ds_read_b128 v[176:179], v151 offset:2048
	ds_read_b128 v[180:183], v151 offset:3072
	s_add_u32 s66, s66, 0x40000
	s_addc_u32 s67, s67, 0
	s_mov_b32 m0, s20
	v_lshl_add_u64 v[246:247], s[66:67], 0, v[134:135]
	ds_read_b128 v[184:187], v150 offset:32768
	ds_read_b128 v[188:191], v150 offset:33792
	ds_read_b128 v[192:195], v150 offset:34816
	ds_read_b128 v[226:229], v150 offset:35840
	ds_read_b128 v[230:233], v150 offset:36864
	ds_read_b128 v[234:237], v150 offset:37888
	ds_read_b128 v[238:241], v150 offset:38912
	ds_read_b128 v[242:245], v150 offset:39936
	global_load_lds_dwordx4 v[246:247], off
	v_lshl_add_u64 v[246:247], s[66:67], 0, v[132:133]
	s_mov_b32 m0, s35
	s_nop 0
	global_load_lds_dwordx4 v[246:247], off
	s_waitcnt vmcnt(8)
	s_waitcnt lgkmcnt(0)
	s_barrier
	s_setprio 1
	s_waitcnt lgkmcnt(0)
	v_mfma_f32_16x16x32_bf16 v[122:125], v[152:155], v[184:187], v[122:125]
	v_mfma_f32_16x16x32_bf16 v[126:129], v[160:163], v[184:187], v[126:129]
	v_mfma_f32_16x16x32_bf16 v[106:109], v[152:155], v[192:195], v[106:109]
	v_mfma_f32_16x16x32_bf16 v[110:113], v[160:163], v[192:195], v[110:113]
	v_mfma_f32_16x16x32_bf16 v[90:93], v[152:155], v[230:233], v[90:93]
	v_mfma_f32_16x16x32_bf16 v[94:97], v[160:163], v[230:233], v[94:97]
	v_mfma_f32_16x16x32_bf16 v[74:77], v[152:155], v[238:241], v[74:77]
	v_mfma_f32_16x16x32_bf16 v[78:81], v[160:163], v[238:241], v[78:81]
	v_mfma_f32_16x16x32_bf16 v[122:125], v[156:159], v[188:191], v[122:125]
	v_mfma_f32_16x16x32_bf16 v[126:129], v[164:167], v[188:191], v[126:129]
	v_mfma_f32_16x16x32_bf16 v[106:109], v[156:159], v[226:229], v[106:109]
	v_mfma_f32_16x16x32_bf16 v[110:113], v[164:167], v[226:229], v[110:113]
	v_mfma_f32_16x16x32_bf16 v[90:93], v[156:159], v[234:237], v[90:93]
	v_mfma_f32_16x16x32_bf16 v[94:97], v[164:167], v[234:237], v[94:97]
	v_mfma_f32_16x16x32_bf16 v[74:77], v[156:159], v[242:245], v[74:77]
	v_mfma_f32_16x16x32_bf16 v[78:81], v[164:167], v[242:245], v[78:81]
	s_setprio 0
	s_setprio 1
	v_mfma_f32_16x16x32_bf16 v[114:117], v[168:171], v[184:187], v[114:117]
	v_mfma_f32_16x16x32_bf16 v[118:121], v[176:179], v[184:187], v[118:121]
	v_mfma_f32_16x16x32_bf16 v[98:101], v[168:171], v[192:195], v[98:101]
	v_mfma_f32_16x16x32_bf16 v[102:105], v[176:179], v[192:195], v[102:105]
	v_mfma_f32_16x16x32_bf16 v[82:85], v[168:171], v[230:233], v[82:85]
	v_mfma_f32_16x16x32_bf16 v[86:89], v[176:179], v[230:233], v[86:89]
	v_mfma_f32_16x16x32_bf16 v[66:69], v[168:171], v[238:241], v[66:69]
	v_mfma_f32_16x16x32_bf16 v[70:73], v[176:179], v[238:241], v[70:73]
	v_mfma_f32_16x16x32_bf16 v[114:117], v[172:175], v[188:191], v[114:117]
	v_mfma_f32_16x16x32_bf16 v[118:121], v[180:183], v[188:191], v[118:121]
	v_mfma_f32_16x16x32_bf16 v[98:101], v[172:175], v[226:229], v[98:101]
	v_mfma_f32_16x16x32_bf16 v[102:105], v[180:183], v[226:229], v[102:105]
	v_mfma_f32_16x16x32_bf16 v[82:85], v[172:175], v[234:237], v[82:85]
	v_mfma_f32_16x16x32_bf16 v[86:89], v[180:183], v[234:237], v[86:89]
	v_mfma_f32_16x16x32_bf16 v[66:69], v[172:175], v[242:245], v[66:69]
	v_mfma_f32_16x16x32_bf16 v[70:73], v[180:183], v[242:245], v[70:73]
	s_setprio 0
	s_barrier
	s_add_i32 s3, s3, s16
	v_lshl_add_u64 v[140:141], v[140:141], 0, s[96:97]
	s_mov_b32 m0, s3
	ds_read_b128 v[184:187], v150 offset:49152
	ds_read_b128 v[188:191], v150 offset:50176
	ds_read_b128 v[192:195], v150 offset:51200
	ds_read_b128 v[226:229], v150 offset:52224
	ds_read_b128 v[230:233], v150 offset:53248
	ds_read_b128 v[234:237], v150 offset:54272
	ds_read_b128 v[238:241], v150 offset:55296
	ds_read_b128 v[242:245], v150 offset:56320
	global_load_lds_dwordx4 v[140:141], off
	s_add_i32 m0, s3, 0x2000
	s_add_u32 s64, s64, 0x40080
	v_lshl_add_u64 v[140:141], v[196:197], 0, s[96:97]
	s_addc_u32 s65, s65, 0
	s_add_i32 s3, s85, s16
	global_load_lds_dwordx4 v[140:141], off
	v_lshl_add_u64 v[140:141], s[64:65], 0, v[144:145]
	s_mov_b32 m0, s3
	s_nop 0
	global_load_lds_dwordx4 v[140:141], off
	v_lshl_add_u64 v[140:141], s[64:65], 0, v[130:131]
	s_add_i32 m0, s3, 0x2000
	s_nop 0
	global_load_lds_dwordx4 v[140:141], off
	v_lshl_add_u64 v[140:141], v[206:207], 0, s[96:97]
	s_mov_b32 m0, s41
	s_nop 0
	global_load_lds_dwordx4 v[140:141], off
	v_lshl_add_u64 v[140:141], v[210:211], 0, s[96:97]
	s_mov_b32 m0, s68
	s_nop 0
	global_load_lds_dwordx4 v[140:141], off
	s_waitcnt vmcnt(8)
	s_waitcnt lgkmcnt(0)
	s_barrier
	s_setprio 1
	s_waitcnt lgkmcnt(0)
	v_mfma_f32_16x16x32_bf16 v[58:61], v[152:155], v[184:187], v[58:61]
	v_mfma_f32_16x16x32_bf16 v[62:65], v[160:163], v[184:187], v[62:65]
	v_mfma_f32_16x16x32_bf16 v[42:45], v[152:155], v[192:195], v[42:45]
	v_mfma_f32_16x16x32_bf16 v[46:49], v[160:163], v[192:195], v[46:49]
	v_mfma_f32_16x16x32_bf16 v[26:29], v[152:155], v[230:233], v[26:29]
	v_mfma_f32_16x16x32_bf16 v[30:33], v[160:163], v[230:233], v[30:33]
	v_mfma_f32_16x16x32_bf16 v[10:13], v[152:155], v[238:241], v[10:13]
	v_mfma_f32_16x16x32_bf16 v[14:17], v[160:163], v[238:241], v[14:17]
	v_mfma_f32_16x16x32_bf16 v[58:61], v[156:159], v[188:191], v[58:61]
	v_mfma_f32_16x16x32_bf16 v[62:65], v[164:167], v[188:191], v[62:65]
	v_mfma_f32_16x16x32_bf16 v[42:45], v[156:159], v[226:229], v[42:45]
	v_mfma_f32_16x16x32_bf16 v[46:49], v[164:167], v[226:229], v[46:49]
	v_mfma_f32_16x16x32_bf16 v[26:29], v[156:159], v[234:237], v[26:29]
	v_mfma_f32_16x16x32_bf16 v[30:33], v[164:167], v[234:237], v[30:33]
	v_mfma_f32_16x16x32_bf16 v[10:13], v[156:159], v[242:245], v[10:13]
	v_mfma_f32_16x16x32_bf16 v[14:17], v[164:167], v[242:245], v[14:17]
	s_setprio 0
	s_setprio 1
	v_mfma_f32_16x16x32_bf16 v[50:53], v[168:171], v[184:187], v[50:53]
	v_mfma_f32_16x16x32_bf16 v[54:57], v[176:179], v[184:187], v[54:57]
	v_mfma_f32_16x16x32_bf16 v[34:37], v[168:171], v[192:195], v[34:37]
	v_mfma_f32_16x16x32_bf16 v[38:41], v[176:179], v[192:195], v[38:41]
	v_mfma_f32_16x16x32_bf16 v[18:21], v[168:171], v[230:233], v[18:21]
	v_mfma_f32_16x16x32_bf16 v[22:25], v[176:179], v[230:233], v[22:25]
	v_mfma_f32_16x16x32_bf16 v[0:3], v[168:171], v[238:241], v[0:3]
	v_mfma_f32_16x16x32_bf16 v[4:7], v[176:179], v[238:241], v[4:7]
	v_mfma_f32_16x16x32_bf16 v[50:53], v[172:175], v[188:191], v[50:53]
	v_mfma_f32_16x16x32_bf16 v[54:57], v[180:183], v[188:191], v[54:57]
	v_mfma_f32_16x16x32_bf16 v[34:37], v[172:175], v[226:229], v[34:37]
	v_mfma_f32_16x16x32_bf16 v[38:41], v[180:183], v[226:229], v[38:41]
	v_mfma_f32_16x16x32_bf16 v[18:21], v[172:175], v[234:237], v[18:21]
	v_mfma_f32_16x16x32_bf16 v[22:25], v[180:183], v[234:237], v[22:25]
	v_mfma_f32_16x16x32_bf16 v[0:3], v[172:175], v[242:245], v[0:3]
	v_mfma_f32_16x16x32_bf16 v[4:7], v[180:183], v[242:245], v[4:7]
	s_setprio 0
	s_barrier
	s_add_i32 s84, s84, 2
	s_add_u32 s74, s74, 0x100
	s_addc_u32 s75, s75, 0
	s_add_u32 s62, s62, 0x100
	s_addc_u32 s63, s63, 0
	s_cmp_gt_u32 s84, 13
	s_cbranch_scc0 .LBB0_159
	s_and_b64 vcc, exec, s[8:9]
	s_cbranch_vccz .LBB0_162
	s_barrier
.LBB0_162:
	s_lshl_b32 s3, s72, 8
	v_mov_b32_e32 v141, v9
	v_mov_b32_e32 v140, v142
	s_add_i32 s3, s3, s38
	s_lshl_b32 s11, s71, 8
	v_add_u32_e32 v152, s3, v141
	s_or_b32 s11, s11, s40
	v_ashrrev_i32_e32 v153, 31, v152
	v_lshl_add_u32 v140, v140, 3, s11
	v_lshlrev_b64 v[152:153], 13, v[152:153]
	v_ashrrev_i32_e32 v141, 31, v140
	v_lshl_add_u64 v[152:153], s[54:55], 0, v[152:153]
	v_max_f32_e32 v122, 0, v122
	v_max_f32_e32 v123, 0, v123
	v_max_f32_e32 v124, 0, v124
	v_max_f32_e32 v125, 0, v125
	v_max_f32_e32 v114, 0, v114
	v_max_f32_e32 v115, 0, v115
	v_max_f32_e32 v116, 0, v116
	v_max_f32_e32 v117, 0, v117
	v_max_f32_e32 v110, 0, v110
	v_max_f32_e32 v106, 0, v106
	v_max_f32_e32 v107, 0, v107
	v_max_f32_e32 v108, 0, v108
	v_lshl_add_u64 v[140:141], v[140:141], 1, v[152:153]
	v_max_f32_e32 v126, 0, v126
	v_max_f32_e32 v127, 0, v127
	v_max_f32_e32 v128, 0, v128
	v_max_f32_e32 v129, 0, v129
	v_mul_f32_e32 v122, v122, v122
	v_mul_f32_e32 v123, v123, v123
	v_mul_f32_e32 v124, v124, v124
	v_mul_f32_e32 v125, v125, v125
	v_max_f32_e32 v118, 0, v118
	v_max_f32_e32 v119, 0, v119
	v_max_f32_e32 v120, 0, v120
	v_max_f32_e32 v121, 0, v121
	v_mul_f32_e32 v114, v114, v114
	v_mul_f32_e32 v115, v115, v115
	v_mul_f32_e32 v116, v116, v116
	v_mul_f32_e32 v117, v117, v117
	v_mul_f32_e32 v110, v110, v110
	v_max_f32_e32 v111, 0, v111
	v_mul_f32_e32 v106, v106, v106
	v_mul_f32_e32 v107, v107, v107
	v_mul_f32_e32 v108, v108, v108
	v_max_f32_e32 v109, 0, v109
	s_mov_b32 s3, 0x20000
	v_mul_f32_e32 v126, v126, v126
	v_mul_f32_e32 v127, v127, v127
	v_mul_f32_e32 v128, v128, v128
	v_mul_f32_e32 v129, v129, v129
	v_cvt_pk_bf16_f32 v122, v122, v123
	v_cvt_pk_bf16_f32 v123, v124, v125
	v_cvt_pk_bf16_f32 v124, v126, v127
	v_cvt_pk_bf16_f32 v125, v128, v129
	global_store_dwordx4 v[140:141], v[122:125], off
	v_mul_f32_e32 v118, v118, v118
	v_mul_f32_e32 v119, v119, v119
	v_mul_f32_e32 v120, v120, v120
	v_mul_f32_e32 v121, v121, v121
	v_cvt_pk_bf16_f32 v114, v114, v115
	v_cvt_pk_bf16_f32 v115, v116, v117
	v_cvt_pk_bf16_f32 v116, v118, v119
	v_cvt_pk_bf16_f32 v117, v120, v121
	global_store_dwordx4 v[140:141], v[114:117], off offset:256
	s_mov_b64 s[62:63], 0x20000
	v_mul_f32_e32 v111, v111, v111
	v_mul_f32_e32 v109, v109, v109
	v_cvt_pk_bf16_f32 v106, v106, v107
	v_cvt_pk_bf16_f32 v107, v108, v109
	v_cvt_pk_bf16_f32 v108, v110, v111
	v_add_co_u32_e32 v110, vcc, s3, v140
	v_max_f32_e32 v98, 0, v98
	v_max_f32_e32 v99, 0, v99
	v_max_f32_e32 v100, 0, v100
	v_max_f32_e32 v101, 0, v101
	v_max_f32_e32 v94, 0, v94
	v_max_f32_e32 v90, 0, v90
	v_max_f32_e32 v91, 0, v91
	v_max_f32_e32 v92, 0, v92
	v_lshl_add_u64 v[114:115], v[140:141], 0, s[62:63]
	v_max_f32_e32 v112, 0, v112
	v_max_f32_e32 v113, 0, v113
	v_addc_co_u32_e32 v111, vcc, 0, v141, vcc
	v_max_f32_e32 v102, 0, v102
	v_max_f32_e32 v103, 0, v103
	v_max_f32_e32 v104, 0, v104
	v_max_f32_e32 v105, 0, v105
	v_mul_f32_e32 v98, v98, v98
	v_mul_f32_e32 v99, v99, v99
	v_mul_f32_e32 v100, v100, v100
	v_mul_f32_e32 v101, v101, v101
	v_mul_f32_e32 v94, v94, v94
	v_max_f32_e32 v95, 0, v95
	v_mul_f32_e32 v90, v90, v90
	v_mul_f32_e32 v91, v91, v91
	v_mul_f32_e32 v92, v92, v92
	v_max_f32_e32 v93, 0, v93
	s_mov_b32 s3, 0x40000
	v_mul_f32_e32 v112, v112, v112
	v_mul_f32_e32 v113, v113, v113
	v_cvt_pk_bf16_f32 v109, v112, v113
	global_store_dwordx4 v[110:111], v[106:109], off
	v_mul_f32_e32 v102, v102, v102
	v_mul_f32_e32 v103, v103, v103
	v_mul_f32_e32 v104, v104, v104
	v_mul_f32_e32 v105, v105, v105
	v_cvt_pk_bf16_f32 v98, v98, v99
	v_cvt_pk_bf16_f32 v99, v100, v101
	v_cvt_pk_bf16_f32 v100, v102, v103
	v_cvt_pk_bf16_f32 v101, v104, v105
	global_store_dwordx4 v[114:115], v[98:101], off offset:256
	s_mov_b64 s[62:63], 0x40000
	v_mul_f32_e32 v95, v95, v95
	v_mul_f32_e32 v93, v93, v93
	v_cvt_pk_bf16_f32 v90, v90, v91
	v_cvt_pk_bf16_f32 v91, v92, v93
	v_cvt_pk_bf16_f32 v92, v94, v95
	v_add_co_u32_e32 v94, vcc, s3, v140
	v_max_f32_e32 v82, 0, v82
	v_max_f32_e32 v83, 0, v83
	v_max_f32_e32 v84, 0, v84
	v_max_f32_e32 v85, 0, v85
	v_max_f32_e32 v78, 0, v78
	v_max_f32_e32 v74, 0, v74
	v_max_f32_e32 v75, 0, v75
	v_max_f32_e32 v76, 0, v76
	v_lshl_add_u64 v[98:99], v[140:141], 0, s[62:63]
	v_max_f32_e32 v96, 0, v96
	v_max_f32_e32 v97, 0, v97
	v_addc_co_u32_e32 v95, vcc, 0, v141, vcc
	v_max_f32_e32 v86, 0, v86
	v_max_f32_e32 v87, 0, v87
	v_max_f32_e32 v88, 0, v88
	v_max_f32_e32 v89, 0, v89
	v_mul_f32_e32 v82, v82, v82
	v_mul_f32_e32 v83, v83, v83
	v_mul_f32_e32 v84, v84, v84
	v_mul_f32_e32 v85, v85, v85
	v_mul_f32_e32 v78, v78, v78
	v_max_f32_e32 v79, 0, v79
	v_mul_f32_e32 v74, v74, v74
	v_mul_f32_e32 v75, v75, v75
	v_mul_f32_e32 v76, v76, v76
	v_max_f32_e32 v77, 0, v77
	s_mov_b32 s3, 0x60000
	v_mul_f32_e32 v96, v96, v96
	v_mul_f32_e32 v97, v97, v97
	v_cvt_pk_bf16_f32 v93, v96, v97
	global_store_dwordx4 v[94:95], v[90:93], off
	v_mul_f32_e32 v86, v86, v86
	v_mul_f32_e32 v87, v87, v87
	v_mul_f32_e32 v88, v88, v88
	v_mul_f32_e32 v89, v89, v89
	v_cvt_pk_bf16_f32 v82, v82, v83
	v_cvt_pk_bf16_f32 v83, v84, v85
	v_cvt_pk_bf16_f32 v84, v86, v87
	v_cvt_pk_bf16_f32 v85, v88, v89
	global_store_dwordx4 v[98:99], v[82:85], off offset:256
	s_mov_b64 s[62:63], 0x60000
	v_mul_f32_e32 v79, v79, v79
	v_mul_f32_e32 v77, v77, v77
	v_cvt_pk_bf16_f32 v74, v74, v75
	v_cvt_pk_bf16_f32 v75, v76, v77
	v_cvt_pk_bf16_f32 v76, v78, v79
	v_add_co_u32_e32 v78, vcc, s3, v140
	v_max_f32_e32 v66, 0, v66
	v_max_f32_e32 v67, 0, v67
	v_max_f32_e32 v68, 0, v68
	v_max_f32_e32 v69, 0, v69
	v_max_f32_e32 v62, 0, v62
	v_max_f32_e32 v58, 0, v58
	v_max_f32_e32 v59, 0, v59
	v_max_f32_e32 v60, 0, v60
	v_lshl_add_u64 v[82:83], v[140:141], 0, s[62:63]
	v_max_f32_e32 v80, 0, v80
	v_max_f32_e32 v81, 0, v81
	v_addc_co_u32_e32 v79, vcc, 0, v141, vcc
	v_max_f32_e32 v70, 0, v70
	v_max_f32_e32 v71, 0, v71
	v_max_f32_e32 v72, 0, v72
	v_max_f32_e32 v73, 0, v73
	v_mul_f32_e32 v66, v66, v66
	v_mul_f32_e32 v67, v67, v67
	v_mul_f32_e32 v68, v68, v68
	v_mul_f32_e32 v69, v69, v69
	v_mul_f32_e32 v62, v62, v62
	v_max_f32_e32 v63, 0, v63
	v_mul_f32_e32 v58, v58, v58
	v_mul_f32_e32 v59, v59, v59
	v_mul_f32_e32 v60, v60, v60
	v_max_f32_e32 v61, 0, v61
	s_mov_b32 s3, 0x100000
	v_mul_f32_e32 v80, v80, v80
	v_mul_f32_e32 v81, v81, v81
	v_cvt_pk_bf16_f32 v77, v80, v81
	global_store_dwordx4 v[78:79], v[74:77], off
	v_mul_f32_e32 v70, v70, v70
	v_mul_f32_e32 v71, v71, v71
	v_mul_f32_e32 v72, v72, v72
	v_mul_f32_e32 v73, v73, v73
	v_cvt_pk_bf16_f32 v66, v66, v67
	v_cvt_pk_bf16_f32 v67, v68, v69
	v_cvt_pk_bf16_f32 v68, v70, v71
	v_cvt_pk_bf16_f32 v69, v72, v73
	global_store_dwordx4 v[82:83], v[66:69], off offset:256
	s_mov_b64 s[62:63], 0x100000
	v_mul_f32_e32 v63, v63, v63
	v_mul_f32_e32 v61, v61, v61
	v_cvt_pk_bf16_f32 v58, v58, v59
	v_cvt_pk_bf16_f32 v59, v60, v61
	v_cvt_pk_bf16_f32 v60, v62, v63
	v_add_co_u32_e32 v62, vcc, s3, v140
	v_max_f32_e32 v50, 0, v50
	v_max_f32_e32 v51, 0, v51
	v_max_f32_e32 v52, 0, v52
	v_max_f32_e32 v53, 0, v53
	v_max_f32_e32 v46, 0, v46
	v_max_f32_e32 v42, 0, v42
	v_max_f32_e32 v43, 0, v43
	v_max_f32_e32 v44, 0, v44
	v_lshl_add_u64 v[66:67], v[140:141], 0, s[62:63]
	v_max_f32_e32 v64, 0, v64
	v_max_f32_e32 v65, 0, v65
	v_addc_co_u32_e32 v63, vcc, 0, v141, vcc
	v_max_f32_e32 v54, 0, v54
	v_max_f32_e32 v55, 0, v55
	v_max_f32_e32 v56, 0, v56
	v_max_f32_e32 v57, 0, v57
	v_mul_f32_e32 v50, v50, v50
	v_mul_f32_e32 v51, v51, v51
	v_mul_f32_e32 v52, v52, v52
	v_mul_f32_e32 v53, v53, v53
	v_mul_f32_e32 v46, v46, v46
	v_max_f32_e32 v47, 0, v47
	v_mul_f32_e32 v42, v42, v42
	v_mul_f32_e32 v43, v43, v43
	v_mul_f32_e32 v44, v44, v44
	v_max_f32_e32 v45, 0, v45
	s_mov_b32 s3, 0x120000
	v_mul_f32_e32 v64, v64, v64
	v_mul_f32_e32 v65, v65, v65
	v_cvt_pk_bf16_f32 v61, v64, v65
	global_store_dwordx4 v[62:63], v[58:61], off
	v_mul_f32_e32 v54, v54, v54
	v_mul_f32_e32 v55, v55, v55
	v_mul_f32_e32 v56, v56, v56
	v_mul_f32_e32 v57, v57, v57
	v_cvt_pk_bf16_f32 v50, v50, v51
	v_cvt_pk_bf16_f32 v51, v52, v53
	v_cvt_pk_bf16_f32 v52, v54, v55
	v_cvt_pk_bf16_f32 v53, v56, v57
	global_store_dwordx4 v[66:67], v[50:53], off offset:256
	s_mov_b64 s[62:63], 0x120000
	v_mul_f32_e32 v47, v47, v47
	v_mul_f32_e32 v45, v45, v45
	v_cvt_pk_bf16_f32 v42, v42, v43
	v_cvt_pk_bf16_f32 v43, v44, v45
	v_cvt_pk_bf16_f32 v44, v46, v47
	v_add_co_u32_e32 v46, vcc, s3, v140
	v_max_f32_e32 v34, 0, v34
	v_max_f32_e32 v35, 0, v35
	v_max_f32_e32 v36, 0, v36
	v_max_f32_e32 v37, 0, v37
	v_max_f32_e32 v30, 0, v30
	v_max_f32_e32 v26, 0, v26
	v_max_f32_e32 v27, 0, v27
	v_max_f32_e32 v28, 0, v28
	v_lshl_add_u64 v[50:51], v[140:141], 0, s[62:63]
	v_max_f32_e32 v48, 0, v48
	v_max_f32_e32 v49, 0, v49
	v_addc_co_u32_e32 v47, vcc, 0, v141, vcc
	v_max_f32_e32 v38, 0, v38
	v_max_f32_e32 v39, 0, v39
	v_max_f32_e32 v40, 0, v40
	v_max_f32_e32 v41, 0, v41
	v_mul_f32_e32 v34, v34, v34
	v_mul_f32_e32 v35, v35, v35
	v_mul_f32_e32 v36, v36, v36
	v_mul_f32_e32 v37, v37, v37
	v_mul_f32_e32 v30, v30, v30
	v_max_f32_e32 v31, 0, v31
	v_mul_f32_e32 v26, v26, v26
	v_mul_f32_e32 v27, v27, v27
	v_mul_f32_e32 v28, v28, v28
	v_max_f32_e32 v29, 0, v29
	s_mov_b32 s3, 0x140000
	v_mul_f32_e32 v48, v48, v48
	v_mul_f32_e32 v49, v49, v49
	v_cvt_pk_bf16_f32 v45, v48, v49
	global_store_dwordx4 v[46:47], v[42:45], off
	v_mul_f32_e32 v38, v38, v38
	v_mul_f32_e32 v39, v39, v39
	v_mul_f32_e32 v40, v40, v40
	v_mul_f32_e32 v41, v41, v41
	v_cvt_pk_bf16_f32 v34, v34, v35
	v_cvt_pk_bf16_f32 v35, v36, v37
	v_cvt_pk_bf16_f32 v36, v38, v39
	v_cvt_pk_bf16_f32 v37, v40, v41
	global_store_dwordx4 v[50:51], v[34:37], off offset:256
	s_mov_b64 s[62:63], 0x140000
	v_mul_f32_e32 v31, v31, v31
	v_mul_f32_e32 v29, v29, v29
	v_cvt_pk_bf16_f32 v26, v26, v27
	v_cvt_pk_bf16_f32 v27, v28, v29
	v_cvt_pk_bf16_f32 v28, v30, v31
	v_add_co_u32_e32 v30, vcc, s3, v140
	v_max_f32_e32 v18, 0, v18
	v_max_f32_e32 v19, 0, v19
	v_max_f32_e32 v20, 0, v20
	v_max_f32_e32 v21, 0, v21
	v_max_f32_e32 v14, 0, v14
	v_max_f32_e32 v10, 0, v10
	v_max_f32_e32 v11, 0, v11
	v_max_f32_e32 v12, 0, v12
	v_lshl_add_u64 v[34:35], v[140:141], 0, s[62:63]
	v_max_f32_e32 v32, 0, v32
	v_max_f32_e32 v33, 0, v33
	v_addc_co_u32_e32 v31, vcc, 0, v141, vcc
	v_max_f32_e32 v22, 0, v22
	v_max_f32_e32 v23, 0, v23
	v_max_f32_e32 v24, 0, v24
	v_max_f32_e32 v25, 0, v25
	v_mul_f32_e32 v18, v18, v18
	v_mul_f32_e32 v19, v19, v19
	v_mul_f32_e32 v20, v20, v20
	v_mul_f32_e32 v21, v21, v21
	v_mul_f32_e32 v14, v14, v14
	v_max_f32_e32 v15, 0, v15
	v_mul_f32_e32 v10, v10, v10
	v_mul_f32_e32 v11, v11, v11
	v_mul_f32_e32 v12, v12, v12
	v_max_f32_e32 v13, 0, v13
	s_mov_b32 s3, 0x160000
	v_mul_f32_e32 v32, v32, v32
	v_mul_f32_e32 v33, v33, v33
	v_cvt_pk_bf16_f32 v29, v32, v33
	global_store_dwordx4 v[30:31], v[26:29], off
	v_mul_f32_e32 v22, v22, v22
	v_mul_f32_e32 v23, v23, v23
	v_mul_f32_e32 v24, v24, v24
	v_mul_f32_e32 v25, v25, v25
	v_cvt_pk_bf16_f32 v18, v18, v19
	v_cvt_pk_bf16_f32 v19, v20, v21
	v_cvt_pk_bf16_f32 v20, v22, v23
	v_cvt_pk_bf16_f32 v21, v24, v25
	global_store_dwordx4 v[34:35], v[18:21], off offset:256
	v_mul_f32_e32 v15, v15, v15
	v_mul_f32_e32 v13, v13, v13
	v_cvt_pk_bf16_f32 v10, v10, v11
	v_cvt_pk_bf16_f32 v11, v12, v13
	v_cvt_pk_bf16_f32 v12, v14, v15
	v_add_co_u32_e32 v14, vcc, s3, v140
	s_mov_b64 s[62:63], 0x160000
	v_addc_co_u32_e32 v15, vcc, 0, v141, vcc
	v_max_f32_e32 v0, 0, v0
	v_max_f32_e32 v1, 0, v1
	v_max_f32_e32 v2, 0, v2
	v_max_f32_e32 v3, 0, v3
	v_lshl_add_u64 v[18:19], v[140:141], 0, s[62:63]
	v_max_f32_e32 v16, 0, v16
	v_max_f32_e32 v17, 0, v17
	v_max_f32_e32 v4, 0, v4
	v_max_f32_e32 v5, 0, v5
	v_max_f32_e32 v6, 0, v6
	v_max_f32_e32 v7, 0, v7
	v_mul_f32_e32 v0, v0, v0
	v_mul_f32_e32 v1, v1, v1
	v_mul_f32_e32 v2, v2, v2
	v_mul_f32_e32 v3, v3, v3
	s_andn2_b64 vcc, exec, s[42:43]
	s_mov_b64 s[42:43], -1
	v_mul_f32_e32 v16, v16, v16
	v_mul_f32_e32 v17, v17, v17
	v_cvt_pk_bf16_f32 v13, v16, v17
	global_store_dwordx4 v[14:15], v[10:13], off
	v_mul_f32_e32 v4, v4, v4
	v_mul_f32_e32 v5, v5, v5
	v_mul_f32_e32 v6, v6, v6
	v_mul_f32_e32 v7, v7, v7
	v_cvt_pk_bf16_f32 v0, v0, v1
	v_cvt_pk_bf16_f32 v1, v2, v3
	v_cvt_pk_bf16_f32 v2, v4, v5
	v_cvt_pk_bf16_f32 v3, v6, v7
	global_store_dwordx4 v[18:19], v[0:3], off offset:256
	s_cbranch_vccnz .LBB0_155
	s_andn2_b64 vcc, exec, s[6:7]
	s_cbranch_vccnz .LBB0_154
	s_barrier
	s_branch .LBB0_154

.LBB0_1240:
	s_ashr_i32 s11, s10, 31
	s_lshl_b64 s[44:45], s[10:11], 19
	s_add_u32 s44, s90, s44
	s_addc_u32 s45, s91, s45
	s_and_b64 s[46:47], s[40:41], exec
	s_cselect_b32 s11, s45, s53
	s_cselect_b32 s12, s44, s52
	s_ashr_i32 s9, s8, 31
	s_lshl_b64 s[46:47], s[8:9], 19
	s_add_u32 s46, s14, s46
	s_addc_u32 s47, s15, s47
	s_and_b64 s[54:55], s[40:41], exec
	s_cselect_b32 s9, s47, s51
	s_cselect_b32 s38, s46, s50
	s_add_u32 s43, s50, 0x100
	s_addc_u32 s49, s51, 0
	s_add_u32 s50, s52, 0x40080
	s_addc_u32 s51, s53, 0
	s_mov_b32 s58, -2
	s_waitcnt lgkmcnt(0)
	s_add_u32 s3, s50, 0xfffc0080
	s_addc_u32 s52, s51, -1
	s_add_i32 s59, 0, 0x10000
	s_cmp_eq_u32 s58, 12
	s_cselect_b32 s55, s11, s52
	s_cselect_b32 s54, s12, s3
	v_add_u32_e32 v142, s59, v153
	s_cselect_b32 s53, s9, s49
	s_cselect_b32 s52, s38, s43
	s_add_i32 s3, 0, 0x14000
	ds_read_b128 v[156:159], v142
	ds_read_b128 v[160:163], v142 offset:1024
	ds_read_b128 v[164:167], v142 offset:2048
	ds_read_b128 v[168:171], v142 offset:3072
	v_add_u32_e32 v142, s3, v153
	ds_read_b128 v[172:175], v142
	ds_read_b128 v[176:179], v142 offset:1024
	ds_read_b128 v[180:183], v142 offset:2048
	ds_read_b128 v[184:187], v142 offset:3072
	v_lshl_add_u64 v[142:143], s[50:51], 0, v[140:141]
	s_add_i32 m0, s17, 0xc000
	ds_read_b128 v[188:191], v154
	ds_read_b128 v[192:195], v154 offset:1024
	ds_read_b128 v[226:229], v154 offset:2048
	ds_read_b128 v[230:233], v154 offset:3072
	ds_read_b128 v[234:237], v154 offset:4096
	ds_read_b128 v[238:241], v154 offset:5120
	ds_read_b128 v[242:245], v154 offset:6144
	ds_read_b128 v[246:249], v154 offset:7168
	global_load_lds_dwordx4 v[142:143], off
	v_lshl_add_u64 v[142:143], s[50:51], 0, v[138:139]
	s_add_i32 m0, s17, 0xe000
	s_nop 0
	global_load_lds_dwordx4 v[142:143], off
	s_waitcnt vmcnt(8)
	s_waitcnt lgkmcnt(0)
	s_barrier
	s_setprio 1
	s_waitcnt lgkmcnt(0)
	v_mfma_f32_16x16x32_bf16 v[126:129], v[156:159], v[188:191], 0
	v_mfma_f32_16x16x32_bf16 v[122:125], v[164:167], v[188:191], 0
	v_mfma_f32_16x16x32_bf16 v[110:113], v[156:159], v[226:229], 0
	v_mfma_f32_16x16x32_bf16 v[106:109], v[164:167], v[226:229], 0
	v_mfma_f32_16x16x32_bf16 v[94:97], v[156:159], v[234:237], 0
	v_mfma_f32_16x16x32_bf16 v[90:93], v[164:167], v[234:237], 0
	v_mfma_f32_16x16x32_bf16 v[78:81], v[156:159], v[242:245], 0
	v_mfma_f32_16x16x32_bf16 v[74:77], v[164:167], v[242:245], 0
	v_mfma_f32_16x16x32_bf16 v[126:129], v[160:163], v[192:195], v[126:129]
	v_mfma_f32_16x16x32_bf16 v[122:125], v[168:171], v[192:195], v[122:125]
	v_mfma_f32_16x16x32_bf16 v[110:113], v[160:163], v[230:233], v[110:113]
	v_mfma_f32_16x16x32_bf16 v[106:109], v[168:171], v[230:233], v[106:109]
	v_mfma_f32_16x16x32_bf16 v[94:97], v[160:163], v[238:241], v[94:97]
	v_mfma_f32_16x16x32_bf16 v[90:93], v[168:171], v[238:241], v[90:93]
	v_mfma_f32_16x16x32_bf16 v[78:81], v[160:163], v[246:249], v[78:81]
	v_mfma_f32_16x16x32_bf16 v[74:77], v[168:171], v[246:249], v[74:77]
	s_setprio 0
	s_setprio 1
	v_mfma_f32_16x16x32_bf16 v[118:121], v[172:175], v[188:191], 0
	v_mfma_f32_16x16x32_bf16 v[114:117], v[180:183], v[188:191], 0
	v_mfma_f32_16x16x32_bf16 v[102:105], v[172:175], v[226:229], 0
	v_mfma_f32_16x16x32_bf16 v[98:101], v[180:183], v[226:229], 0
	v_mfma_f32_16x16x32_bf16 v[86:89], v[172:175], v[234:237], 0
	v_mfma_f32_16x16x32_bf16 v[82:85], v[180:183], v[234:237], 0
	v_mfma_f32_16x16x32_bf16 v[70:73], v[172:175], v[242:245], 0
	v_mfma_f32_16x16x32_bf16 v[66:69], v[180:183], v[242:245], 0
	v_mfma_f32_16x16x32_bf16 v[118:121], v[176:179], v[192:195], v[118:121]
	v_mfma_f32_16x16x32_bf16 v[114:117], v[184:187], v[192:195], v[114:117]
	v_mfma_f32_16x16x32_bf16 v[102:105], v[176:179], v[230:233], v[102:105]
	v_mfma_f32_16x16x32_bf16 v[98:101], v[184:187], v[230:233], v[98:101]
	v_mfma_f32_16x16x32_bf16 v[86:89], v[176:179], v[238:241], v[86:89]
	v_mfma_f32_16x16x32_bf16 v[82:85], v[184:187], v[238:241], v[82:85]
	v_mfma_f32_16x16x32_bf16 v[70:73], v[176:179], v[246:249], v[70:73]
	v_mfma_f32_16x16x32_bf16 v[66:69], v[184:187], v[246:249], v[66:69]
	s_setprio 0
	s_barrier
	s_add_i32 s59, s59, s16
	v_lshl_add_u64 v[142:143], s[52:53], 0, v[132:133]
	s_mov_b32 m0, s59
	ds_read_b128 v[188:191], v154 offset:16384
	ds_read_b128 v[192:195], v154 offset:17408
	ds_read_b128 v[226:229], v154 offset:18432
	ds_read_b128 v[230:233], v154 offset:19456
	ds_read_b128 v[234:237], v154 offset:20480
	ds_read_b128 v[238:241], v154 offset:21504
	ds_read_b128 v[242:245], v154 offset:22528
	ds_read_b128 v[246:249], v154 offset:23552
	global_load_lds_dwordx4 v[142:143], off
	s_add_i32 m0, s59, 0x2000
	s_add_u32 s60, s52, 0x40000
	v_lshl_add_u64 v[150:151], s[52:53], 0, v[136:137]
	s_addc_u32 s61, s53, 0
	s_add_i32 s3, s3, s16
	global_load_lds_dwordx4 v[150:151], off
	v_lshl_add_u64 v[196:197], s[60:61], 0, v[132:133]
	s_mov_b32 m0, s3
	v_lshl_add_u64 v[250:251], s[54:55], 0, v[134:135]
	global_load_lds_dwordx4 v[196:197], off
	v_lshl_add_u64 v[196:197], s[60:61], 0, v[136:137]
	s_add_i32 m0, s3, 0x2000
	s_nop 0
	global_load_lds_dwordx4 v[196:197], off
	v_lshl_add_u64 v[196:197], s[54:55], 0, v[130:131]
	s_mov_b32 m0, s17
	s_nop 0
	global_load_lds_dwordx4 v[196:197], off
	s_mov_b32 m0, s18
	s_nop 0
	global_load_lds_dwordx4 v[250:251], off
	s_waitcnt vmcnt(8)
	s_waitcnt lgkmcnt(0)
	s_barrier
	s_setprio 1
	s_waitcnt lgkmcnt(0)
	v_mfma_f32_16x16x32_bf16 v[62:65], v[156:159], v[188:191], 0
	v_mfma_f32_16x16x32_bf16 v[58:61], v[164:167], v[188:191], 0
	v_mfma_f32_16x16x32_bf16 v[46:49], v[156:159], v[226:229], 0
	v_mfma_f32_16x16x32_bf16 v[42:45], v[164:167], v[226:229], 0
	v_mfma_f32_16x16x32_bf16 v[30:33], v[156:159], v[234:237], 0
	v_mfma_f32_16x16x32_bf16 v[26:29], v[164:167], v[234:237], 0
	v_mfma_f32_16x16x32_bf16 v[14:17], v[156:159], v[242:245], 0
	v_mfma_f32_16x16x32_bf16 v[10:13], v[164:167], v[242:245], 0
	v_mfma_f32_16x16x32_bf16 v[62:65], v[160:163], v[192:195], v[62:65]
	v_mfma_f32_16x16x32_bf16 v[58:61], v[168:171], v[192:195], v[58:61]
	v_mfma_f32_16x16x32_bf16 v[46:49], v[160:163], v[230:233], v[46:49]
	v_mfma_f32_16x16x32_bf16 v[42:45], v[168:171], v[230:233], v[42:45]
	v_mfma_f32_16x16x32_bf16 v[30:33], v[160:163], v[238:241], v[30:33]
	v_mfma_f32_16x16x32_bf16 v[26:29], v[168:171], v[238:241], v[26:29]
	v_mfma_f32_16x16x32_bf16 v[14:17], v[160:163], v[246:249], v[14:17]
	v_mfma_f32_16x16x32_bf16 v[10:13], v[168:171], v[246:249], v[10:13]
	s_setprio 0
	s_setprio 1
	v_mfma_f32_16x16x32_bf16 v[54:57], v[172:175], v[188:191], 0
	v_mfma_f32_16x16x32_bf16 v[50:53], v[180:183], v[188:191], 0
	v_mfma_f32_16x16x32_bf16 v[38:41], v[172:175], v[226:229], 0
	v_mfma_f32_16x16x32_bf16 v[34:37], v[180:183], v[226:229], 0
	v_mfma_f32_16x16x32_bf16 v[22:25], v[172:175], v[234:237], 0
	v_mfma_f32_16x16x32_bf16 v[18:21], v[180:183], v[234:237], 0
	v_mfma_f32_16x16x32_bf16 v[4:7], v[172:175], v[242:245], 0
	v_mfma_f32_16x16x32_bf16 v[0:3], v[180:183], v[242:245], 0
	v_mfma_f32_16x16x32_bf16 v[54:57], v[176:179], v[192:195], v[54:57]
	v_mfma_f32_16x16x32_bf16 v[50:53], v[184:187], v[192:195], v[50:53]
	v_mfma_f32_16x16x32_bf16 v[38:41], v[176:179], v[230:233], v[38:41]
	v_mfma_f32_16x16x32_bf16 v[34:37], v[184:187], v[230:233], v[34:37]
	v_mfma_f32_16x16x32_bf16 v[22:25], v[176:179], v[238:241], v[22:25]
	v_mfma_f32_16x16x32_bf16 v[18:21], v[184:187], v[238:241], v[18:21]
	v_mfma_f32_16x16x32_bf16 v[4:7], v[176:179], v[246:249], v[4:7]
	v_mfma_f32_16x16x32_bf16 v[0:3], v[184:187], v[246:249], v[0:3]
	s_setprio 0
	s_barrier
	s_branch .Lgemm_mid_2

.Lgemm_mid_2:
	s_add_i32 s3, 0, 0x18000
	v_add_u32_e32 v144, s3, v153
	s_add_i32 s59, 0, 0x1c000
	ds_read_b128 v[156:159], v144
	ds_read_b128 v[160:163], v144 offset:1024
	ds_read_b128 v[164:167], v144 offset:2048
	ds_read_b128 v[168:171], v144 offset:3072
	v_add_u32_e32 v144, s59, v153
	ds_read_b128 v[172:175], v144
	ds_read_b128 v[176:179], v144 offset:1024
	ds_read_b128 v[180:183], v144 offset:2048
	ds_read_b128 v[184:187], v144 offset:3072
	s_add_u32 s54, s54, 0x40000
	s_addc_u32 s55, s55, 0
	s_mov_b32 m0, s20
	v_lshl_add_u64 v[206:207], s[54:55], 0, v[130:131]
	ds_read_b128 v[188:191], v154 offset:32768
	ds_read_b128 v[192:195], v154 offset:33792
	ds_read_b128 v[226:229], v154 offset:34816
	ds_read_b128 v[230:233], v154 offset:35840
	ds_read_b128 v[234:237], v154 offset:36864
	ds_read_b128 v[238:241], v154 offset:37888
	ds_read_b128 v[242:245], v154 offset:38912
	ds_read_b128 v[246:249], v154 offset:39936
	global_load_lds_dwordx4 v[206:207], off
	v_lshl_add_u64 v[206:207], s[54:55], 0, v[134:135]
	s_mov_b32 m0, s35
	s_nop 0
	global_load_lds_dwordx4 v[206:207], off
	s_waitcnt vmcnt(8)
	s_waitcnt lgkmcnt(0)
	s_barrier
	s_setprio 1
	s_waitcnt lgkmcnt(0)
	v_mfma_f32_16x16x32_bf16 v[126:129], v[156:159], v[188:191], v[126:129]
	v_mfma_f32_16x16x32_bf16 v[122:125], v[164:167], v[188:191], v[122:125]
	v_mfma_f32_16x16x32_bf16 v[110:113], v[156:159], v[226:229], v[110:113]
	v_mfma_f32_16x16x32_bf16 v[106:109], v[164:167], v[226:229], v[106:109]
	v_mfma_f32_16x16x32_bf16 v[94:97], v[156:159], v[234:237], v[94:97]
	v_mfma_f32_16x16x32_bf16 v[90:93], v[164:167], v[234:237], v[90:93]
	v_mfma_f32_16x16x32_bf16 v[78:81], v[156:159], v[242:245], v[78:81]
	v_mfma_f32_16x16x32_bf16 v[74:77], v[164:167], v[242:245], v[74:77]
	v_mfma_f32_16x16x32_bf16 v[126:129], v[160:163], v[192:195], v[126:129]
	v_mfma_f32_16x16x32_bf16 v[122:125], v[168:171], v[192:195], v[122:125]
	v_mfma_f32_16x16x32_bf16 v[110:113], v[160:163], v[230:233], v[110:113]
	v_mfma_f32_16x16x32_bf16 v[106:109], v[168:171], v[230:233], v[106:109]
	v_mfma_f32_16x16x32_bf16 v[94:97], v[160:163], v[238:241], v[94:97]
	v_mfma_f32_16x16x32_bf16 v[90:93], v[168:171], v[238:241], v[90:93]
	v_mfma_f32_16x16x32_bf16 v[78:81], v[160:163], v[246:249], v[78:81]
	v_mfma_f32_16x16x32_bf16 v[74:77], v[168:171], v[246:249], v[74:77]
	s_setprio 0
	s_setprio 1
	v_mfma_f32_16x16x32_bf16 v[118:121], v[172:175], v[188:191], v[118:121]
	v_mfma_f32_16x16x32_bf16 v[114:117], v[180:183], v[188:191], v[114:117]
	v_mfma_f32_16x16x32_bf16 v[102:105], v[172:175], v[226:229], v[102:105]
	v_mfma_f32_16x16x32_bf16 v[98:101], v[180:183], v[226:229], v[98:101]
	v_mfma_f32_16x16x32_bf16 v[86:89], v[172:175], v[234:237], v[86:89]
	v_mfma_f32_16x16x32_bf16 v[82:85], v[180:183], v[234:237], v[82:85]
	v_mfma_f32_16x16x32_bf16 v[70:73], v[172:175], v[242:245], v[70:73]
	v_mfma_f32_16x16x32_bf16 v[66:69], v[180:183], v[242:245], v[66:69]
	v_mfma_f32_16x16x32_bf16 v[118:121], v[176:179], v[192:195], v[118:121]
	v_mfma_f32_16x16x32_bf16 v[114:117], v[184:187], v[192:195], v[114:117]
	v_mfma_f32_16x16x32_bf16 v[102:105], v[176:179], v[230:233], v[102:105]
	v_mfma_f32_16x16x32_bf16 v[98:101], v[184:187], v[230:233], v[98:101]
	v_mfma_f32_16x16x32_bf16 v[86:89], v[176:179], v[238:241], v[86:89]
	v_mfma_f32_16x16x32_bf16 v[82:85], v[184:187], v[238:241], v[82:85]
	v_mfma_f32_16x16x32_bf16 v[70:73], v[176:179], v[246:249], v[70:73]
	v_mfma_f32_16x16x32_bf16 v[66:69], v[184:187], v[246:249], v[66:69]
	s_setprio 0
	s_barrier
	s_add_i32 s3, s3, s16
	v_lshl_add_u64 v[142:143], v[142:143], 0, s[96:97]
	s_mov_b32 m0, s3
	ds_read_b128 v[188:191], v154 offset:49152
	ds_read_b128 v[192:195], v154 offset:50176
	ds_read_b128 v[226:229], v154 offset:51200
	ds_read_b128 v[230:233], v154 offset:52224
	ds_read_b128 v[234:237], v154 offset:53248
	ds_read_b128 v[238:241], v154 offset:54272
	ds_read_b128 v[242:245], v154 offset:55296
	ds_read_b128 v[246:249], v154 offset:56320
	global_load_lds_dwordx4 v[142:143], off
	s_add_i32 m0, s3, 0x2000
	s_add_u32 s52, s52, 0x40080
	v_lshl_add_u64 v[142:143], v[150:151], 0, s[96:97]
	s_addc_u32 s53, s53, 0
	s_add_i32 s3, s59, s16
	global_load_lds_dwordx4 v[142:143], off
	v_lshl_add_u64 v[142:143], s[52:53], 0, v[132:133]
	s_mov_b32 m0, s3
	s_nop 0
	global_load_lds_dwordx4 v[142:143], off
	v_lshl_add_u64 v[142:143], s[52:53], 0, v[136:137]
	s_add_i32 m0, s3, 0x2000
	s_nop 0
	global_load_lds_dwordx4 v[142:143], off
	v_lshl_add_u64 v[142:143], v[196:197], 0, s[96:97]
	s_mov_b32 m0, s64
	s_nop 0
	global_load_lds_dwordx4 v[142:143], off
	v_lshl_add_u64 v[142:143], v[250:251], 0, s[96:97]
	s_mov_b32 m0, s65
	s_nop 0
	global_load_lds_dwordx4 v[142:143], off
	s_waitcnt vmcnt(8)
	s_waitcnt lgkmcnt(0)
	s_barrier
	s_setprio 1
	s_waitcnt lgkmcnt(0)
	v_mfma_f32_16x16x32_bf16 v[62:65], v[156:159], v[188:191], v[62:65]
	v_mfma_f32_16x16x32_bf16 v[58:61], v[164:167], v[188:191], v[58:61]
	v_mfma_f32_16x16x32_bf16 v[46:49], v[156:159], v[226:229], v[46:49]
	v_mfma_f32_16x16x32_bf16 v[42:45], v[164:167], v[226:229], v[42:45]
	v_mfma_f32_16x16x32_bf16 v[30:33], v[156:159], v[234:237], v[30:33]
	v_mfma_f32_16x16x32_bf16 v[26:29], v[164:167], v[234:237], v[26:29]
	v_mfma_f32_16x16x32_bf16 v[14:17], v[156:159], v[242:245], v[14:17]
	v_mfma_f32_16x16x32_bf16 v[10:13], v[164:167], v[242:245], v[10:13]
	v_mfma_f32_16x16x32_bf16 v[62:65], v[160:163], v[192:195], v[62:65]
	v_mfma_f32_16x16x32_bf16 v[58:61], v[168:171], v[192:195], v[58:61]
	v_mfma_f32_16x16x32_bf16 v[46:49], v[160:163], v[230:233], v[46:49]
	v_mfma_f32_16x16x32_bf16 v[42:45], v[168:171], v[230:233], v[42:45]
	v_mfma_f32_16x16x32_bf16 v[30:33], v[160:163], v[238:241], v[30:33]
	v_mfma_f32_16x16x32_bf16 v[26:29], v[168:171], v[238:241], v[26:29]
	v_mfma_f32_16x16x32_bf16 v[14:17], v[160:163], v[246:249], v[14:17]
	v_mfma_f32_16x16x32_bf16 v[10:13], v[168:171], v[246:249], v[10:13]
	s_setprio 0
	s_setprio 1
	v_mfma_f32_16x16x32_bf16 v[54:57], v[172:175], v[188:191], v[54:57]
	v_mfma_f32_16x16x32_bf16 v[50:53], v[180:183], v[188:191], v[50:53]
	v_mfma_f32_16x16x32_bf16 v[38:41], v[172:175], v[226:229], v[38:41]
	v_mfma_f32_16x16x32_bf16 v[34:37], v[180:183], v[226:229], v[34:37]
	v_mfma_f32_16x16x32_bf16 v[22:25], v[172:175], v[234:237], v[22:25]
	v_mfma_f32_16x16x32_bf16 v[18:21], v[180:183], v[234:237], v[18:21]
	v_mfma_f32_16x16x32_bf16 v[4:7], v[172:175], v[242:245], v[4:7]
	v_mfma_f32_16x16x32_bf16 v[0:3], v[180:183], v[242:245], v[0:3]
	v_mfma_f32_16x16x32_bf16 v[54:57], v[176:179], v[192:195], v[54:57]
	v_mfma_f32_16x16x32_bf16 v[50:53], v[184:187], v[192:195], v[50:53]
	v_mfma_f32_16x16x32_bf16 v[38:41], v[176:179], v[230:233], v[38:41]
	v_mfma_f32_16x16x32_bf16 v[34:37], v[184:187], v[230:233], v[34:37]
	v_mfma_f32_16x16x32_bf16 v[22:25], v[176:179], v[238:241], v[22:25]
	v_mfma_f32_16x16x32_bf16 v[18:21], v[184:187], v[238:241], v[18:21]
	v_mfma_f32_16x16x32_bf16 v[4:7], v[176:179], v[246:249], v[4:7]
	v_mfma_f32_16x16x32_bf16 v[0:3], v[184:187], v[246:249], v[0:3]
	s_setprio 0
	s_barrier
	s_add_i32 s58, s58, 2
	s_add_u32 s43, s43, 0x100
	s_addc_u32 s49, s49, 0
	s_add_u32 s50, s50, 0x100
	s_addc_u32 s51, s51, 0
	s_cmp_gt_u32 s58, 13
	s_cbranch_scc0 .LBB0_1241
	s_and_b64 vcc, exec, s[6:7]
	s_cbranch_vccz .LBB0_1244
	s_barrier
